# ret_local (P2) staging loads de-serialized
# baseline (speedup 1.0000x reference)
; DI void unpack8(uint4 v, float* f) { f[0] = bflo(v.x); f[1] = bfhi(v.x); f[2] = bflo(v.y); f[3] = bfhi(v.y); f[4] = bflo(v.z); f[5] = bfhi(v.z); f[6] = bflo(v.w); f[7] = bfhi(v.w); }
; DI float ex2(float x) { return __builtin_amdgcn_exp2f(x); }
; DI void norm_unit(const Params& p, int layer, int half, int nu, int tid) { norm_rows(p, layer, half * HROWS + nu * 64, 64, 0, 8, tid); }
; #define otid() otid_(wbase)
; DI void ret_local_unit(const Params& p, int hf, int bl, int c, int hd, unsigned char* shm, int tid) {
;   unsigned char* wsb = ows(p);
;   bf16_t* sK = (bf16_t*)shm; bf16_t* sV = sK + 128 * LD;
;   const bf16_t* projb = (const bf16_t*)(wsb + WS_PROJ) + (size_t)bl * SEQ * NP;
;   const float2* cs = (const float2*)(wsb + WS_CS) + (size_t)((hf * 2 + bl) * SEQ + c * 128) * 64;
;   const float lg = logf(1.0f - ex2(-5.0f - (float)hd));
; #pragma unroll
;   for (int it = 0; it < 2; ++it) {
;     const int idx = tid + it * NTHR, j = idx >> 3, dg = idx & 7;
;     const bf16_t* base = projb + (size_t)(c * 128 + j) * NP;
;     float k1[8], k2[8]; unpack8(*(const uint4*)(base + C_RK + hd * 128 + dg * 8), k1); unpack8(*(const uint4*)(base + C_RK + hd * 128 + 64 + dg * 8), k2);
;     const float w = __expf(lg * (float)(127 - j)) * 0.08838834764831845f;
; __global__ void __launch_bounds__(NTHR) mega(Params p) {
;     ...
;         int* my = ctr + 8 + phase_id;
;         for (;;) {
;           __syncthreads();
;           if (otid() == 0) s_unit = atomicAdd(my, 1);
;           __syncthreads();
;           const int u0 = s_unit;
;           const int n_fill = (hf == 0 && layer > 0) ? 256 : 0;
;           int u = u0;
;           if (u >= 784 + n_fill) break;
;           if (u >= 16 && u < 16 + n_fill) { norm_unit(p, layer, 1, u - 16, otid()); continue; }
;           if (u >= 16) u -= n_fill;
;           if (u < 16) fox_cumsum_unit(p, hf, u >> 3, u & 7, shm, otid());
;           else if (u < 272) { const int k = u - 16; ssd_local_unit(p, layer, hf, k >> 7, (k >> 1) & 63, k & 1, shm, otid()); }
;           else { const int k = u - 272; ret_local_unit(p, hf, k >> 8, (k >> 2) & 63, k & 3, shm, otid()); }
.LBB0_241:
	s_or_b64 exec, exec, s[0:1]
	s_waitcnt lgkmcnt(0)
	s_barrier
	ds_read_b32 v0, v161 offset:16
	s_mov_b64 s[0:1], -1
	s_waitcnt lgkmcnt(0)
	v_cmp_le_i32_e32 vcc, s56, v0
	v_readfirstlane_b32 s58, v0
	s_cbranch_vccnz .LBB0_236
	s_cmp_gt_i32 s58, 15
	s_cselect_b64 s[0:1], -1, 0
	s_cmp_lt_i32 s58, s57
	s_cselect_b64 s[4:5], -1, 0
	s_and_b64 s[4:5], s[0:1], s[4:5]
	s_andn2_b64 vcc, exec, s[4:5]
	s_mov_b64 s[4:5], -1
	s_cbranch_vccz .LBB0_353
	s_and_b64 s[0:1], s[0:1], exec
	s_cselect_b32 s0, s13, 0
	s_sub_i32 s24, s58, s0
	s_cmp_gt_i32 s24, 15
	s_mov_b64 s[0:1], -1
	s_cbranch_scc0 .LBB0_312
	s_cmpk_gt_u32 s24, 0x10f
	s_cbranch_scc0 .LBB0_246
	s_add_i32 s8, s24, 0xfffffef0
	s_lshr_b32 s4, s8, 8
	s_mul_i32 s2, s4, 0x3400000
	s_bfe_u32 s10, s8, 0x60002
	s_and_b32 s9, s58, 3
	s_lshl_b64 s[0:1], s[2:3], 1
	s_add_u32 s6, s38, s0
	s_addc_u32 s7, s39, s1
	s_lshl_b32 s0, s4, 13
	v_cvt_f32_ubyte0_e32 v0, s9
	s_add_i32 s0, s0, s68
	s_lshl_b32 s11, s10, 7
	v_sub_f32_e32 v0, 0xc0a00000, v0
	s_or_b32 s0, s0, s11
	v_exp_f32_e32 v0, v0
	s_lshl_b32 s2, s0, 6
	s_lshl_b64 s[0:1], s[2:3], 3
	v_readlane_b32 s2, v252, 45
	s_add_u32 s4, s2, s0
	v_readlane_b32 s0, v252, 46
	s_addc_u32 s5, s0, s1
	v_sub_f32_e32 v0, 1.0, v0
	s_mov_b32 s0, 0x800000
	v_cmp_gt_f32_e32 vcc, s0, v0
	s_and_b64 s[0:1], vcc, exec
	s_cselect_b32 s0, 32, 0
	v_ldexp_f32 v0, v0, s0
	v_log_f32_e32 v0, v0
	s_mov_b32 s0, 0x3f317217
	v_mov_b32_e32 v18, v163
	v_mul_f32_e32 v1, 0x3f317217, v0
	v_fma_f32 v1, v0, s0, -v1
	v_fmac_f32_e32 v1, 0x3377d1cf, v0
	s_mov_b32 s0, 0x7f800000
	v_fmac_f32_e32 v1, 0x3f317217, v0
	v_cmp_lt_f32_e64 s[0:1], |v0|, s0
	v_ashrrev_i32_e32 v13, 3, v18
	v_mov_b64_e32 v[14:15], s[6:7]
	v_cndmask_b32_e64 v0, v0, v1, s[0:1]
	v_cndmask_b32_e32 v1, 0, v201, vcc
	v_sub_f32_e32 v21, v0, v1
	v_and_b32_e32 v0, 7, v18
	v_lshlrev_b32_e32 v20, 3, v0
	v_lshlrev_b32_e32 v160, 4, v0
	v_lshlrev_b32_e32 v12, 5, v0
	v_add_u32_e32 v0, s11, v13
	v_mad_i64_i32 v[0:1], s[0:1], v0, s65, v[14:15]
	s_lshl_b32 s2, s9, 8
	v_lshl_add_u64 v[16:17], v[0:1], 0, s[2:3]
	v_lshl_add_u64 v[4:5], v[16:17], 0, v[160:161]
	v_lshl_add_u64 v[208:209], v[16:17], 0, v[160:161]
	global_load_dwordx4 v[100:103], v[208:209], off offset:1024
	global_load_dwordx4 v[104:107], v[208:209], off offset:1152
	v_lshl_or_b32 v210, v13, 6, v20
	v_mov_b32_e32 v211, v161
	v_lshl_add_u64 v[210:211], v[210:211], 3, s[4:5]
	global_load_dwordx4 v[108:111], v[210:211], off offset:48
	global_load_dwordx4 v[112:115], v[210:211], off offset:32
	global_load_dwordx4 v[116:119], v[210:211], off offset:16
	global_load_dwordx4 v[120:123], v[210:211], off
	v_mov_b32_e32 v212, v12
	v_mov_b32_e32 v213, v161
	v_lshl_add_u64 v[212:213], v[16:17], 0, v[212:213]
	global_load_dwordx4 v[124:127], v[212:213], off offset:2048
	global_load_dwordx4 v[128:131], v[212:213], off offset:2064
	v_add_u32_e32 v222, 64, v13
	v_add_u32_e32 v223, s11, v222
	v_mad_i64_i32 v[214:215], s[0:1], v223, s65, v[14:15]
	v_lshl_add_u64 v[214:215], v[214:215], 0, s[2:3]
	v_lshl_add_u64 v[216:217], v[214:215], 0, v[160:161]
	global_load_dwordx4 v[132:135], v[216:217], off offset:1024
	global_load_dwordx4 v[136:139], v[216:217], off offset:1152
	v_lshl_or_b32 v218, v222, 6, v20
	v_mov_b32_e32 v219, v161
	v_lshl_add_u64 v[218:219], v[218:219], 3, s[4:5]
	global_load_dwordx4 v[140:143], v[218:219], off offset:48
	global_load_dwordx4 v[144:147], v[218:219], off offset:32
	global_load_dwordx4 v[148:151], v[218:219], off offset:16
	global_load_dwordx4 v[152:155], v[218:219], off
	v_mov_b32_e32 v220, v12
	v_mov_b32_e32 v221, v161
	v_lshl_add_u64 v[220:221], v[214:215], 0, v[220:221]
	global_load_dwordx4 v[156:159], v[220:221], off offset:2048
	global_load_dwordx4 v[204:207], v[220:221], off offset:2064
	v_add_u32_e32 v19, 32, v12
	s_waitcnt vmcnt(15)
	v_mov_b32_e32 v0, v100
	v_mov_b32_e32 v1, v101
	v_mov_b32_e32 v2, v102
	v_mov_b32_e32 v3, v103
	v_lshlrev_b32_e32 v26, 16, v0
	v_and_b32_e32 v27, 0xffff0000, v0
	v_lshlrev_b32_e32 v28, 16, v1
	v_and_b32_e32 v29, 0xffff0000, v1
	v_lshlrev_b32_e32 v30, 16, v2
	v_and_b32_e32 v31, 0xffff0000, v2
	v_lshlrev_b32_e32 v32, 16, v3
	v_and_b32_e32 v33, 0xffff0000, v3
	s_waitcnt vmcnt(14)
	v_mov_b32_e32 v0, v104
	v_mov_b32_e32 v1, v105
	v_mov_b32_e32 v2, v106
	v_mov_b32_e32 v3, v107
	v_lshlrev_b32_e32 v34, 16, v0
	v_and_b32_e32 v35, 0xffff0000, v0
	v_sub_u32_e32 v0, 0x7f, v13
	v_cvt_f32_i32_e32 v0, v0
	v_lshlrev_b32_e32 v36, 16, v1
	v_and_b32_e32 v37, 0xffff0000, v1
	v_lshlrev_b32_e32 v38, 16, v2
	v_mul_f32_e32 v0, v21, v0
	v_mul_f32_e32 v0, 0x3fb8aa3b, v0
	v_exp_f32_e32 v0, v0
	v_and_b32_e32 v39, 0xffff0000, v2
	v_lshlrev_b32_e32 v40, 16, v3
	v_and_b32_e32 v41, 0xffff0000, v3
	v_mul_f32_e32 v42, 0x3db504f3, v0
	v_lshl_or_b32 v0, v13, 6, v20
	v_ashrrev_i32_e32 v1, 31, v0
	v_lshl_add_u64 v[22:23], v[0:1], 3, s[4:5]
	s_nop 0
	s_waitcnt vmcnt(10)
; DI void unpack8(uint4 v, float* f) { f[0] = bflo(v.x); f[1] = bfhi(v.x); f[2] = bflo(v.y); f[3] = bfhi(v.y); f[4] = bflo(v.z); f[5] = bfhi(v.z); f[6] = bflo(v.w); f[7] = bfhi(v.w); }
; DI uint4 pack8(const float* f) { uint4 r; r.x = pk2(f[0], f[1]); r.y = pk2(f[2], f[3]); r.z = pk2(f[4], f[5]); r.w = pk2(f[6], f[7]); return r; }
; DI void ret_local_unit(const Params& p, int hf, int bl, int c, int hd, unsigned char* shm, int tid) {
;     ...
;   for (int it = 0; it < 2; ++it) {
;     const int idx = tid + it * NTHR, j = idx >> 3, dg = idx & 7;
;     const bf16_t* base = projb + (size_t)(c * 128 + j) * NP;
;     float k1[8], k2[8]; unpack8(*(const uint4*)(base + C_RK + hd * 128 + dg * 8), k1); unpack8(*(const uint4*)(base + C_RK + hd * 128 + 64 + dg * 8), k2);
;     const float w = __expf(lg * (float)(127 - j)) * 0.08838834764831845f;
;     float o1[8], o2[8];
; #pragma unroll
;     for (int e = 0; e < 8; ++e) {
;       const float2 t = cs[j * 64 + dg * 8 + e];
;       o1[e] = (k1[e] * t.x - k2[e] * t.y) * w; o2[e] = (k1[e] * t.y + k2[e] * t.x) * w;
;     }
;     *(uint4*)(sK + j * LD + dg * 8) = pack8(o1); *(uint4*)(sK + j * LD + 64 + dg * 8) = pack8(o2);
;     *(uint4*)(sV + j * LD + dg * 16) = *(const uint4*)(base + C_RV + hd * 128 + dg * 16);
;     *(uint4*)(sV + j * LD + dg * 16 + 8) = *(const uint4*)(base + C_RV + hd * 128 + dg * 16 + 8);
;   }
	v_mov_b32_e32 v0, v108
	v_mov_b32_e32 v1, v109
	v_mov_b32_e32 v2, v110
	v_mov_b32_e32 v3, v111
	v_mov_b32_e32 v4, v112
	v_mov_b32_e32 v5, v113
	v_mov_b32_e32 v6, v114
	v_mov_b32_e32 v7, v115
	v_mov_b32_e32 v8, v116
	v_mov_b32_e32 v9, v117
	v_mov_b32_e32 v10, v118
	v_mov_b32_e32 v11, v119
	v_mov_b32_e32 v22, v120
	v_mov_b32_e32 v23, v121
	v_mov_b32_e32 v24, v122
	v_mov_b32_e32 v25, v123
	v_mul_f32_e32 v43, v23, v34
	v_mul_f32_e32 v23, v23, v26
	v_fmac_f32_e32 v23, v22, v34
	v_fma_f32 v43, v22, v26, -v43
	v_mul_f32_e32 v22, v42, v23
	v_mul_f32_e32 v23, v25, v35
	v_mul_f32_e32 v25, v25, v27
	v_fmac_f32_e32 v25, v24, v35
	v_fma_f32 v23, v24, v27, -v23
	v_mul_f32_e32 v24, v42, v25
	v_mul_f32_e32 v25, v9, v36
	v_mul_f32_e32 v9, v9, v28
	v_fmac_f32_e32 v9, v8, v36
	v_fma_f32 v25, v8, v28, -v25
	v_mul_f32_e32 v8, v42, v9
	v_mul_f32_e32 v9, v11, v37
	v_mul_f32_e32 v11, v11, v29
	v_fmac_f32_e32 v11, v10, v37
	v_fma_f32 v9, v10, v29, -v9
	v_mul_f32_e32 v10, v42, v11
	v_mul_f32_e32 v11, v5, v38
	v_mul_f32_e32 v5, v5, v30
	v_fmac_f32_e32 v5, v4, v38
	v_fma_f32 v11, v4, v30, -v11
	v_mul_f32_e32 v4, v42, v5
	v_mul_f32_e32 v5, v7, v39
	v_mul_f32_e32 v7, v7, v31
	v_fmac_f32_e32 v7, v6, v39
	v_fma_f32 v5, v6, v31, -v5
	v_mul_f32_e32 v6, v42, v7
	v_mul_f32_e32 v7, v1, v40
	v_mul_f32_e32 v1, v1, v32
	v_fma_f32 v7, v0, v32, -v7
	v_fmac_f32_e32 v1, v0, v40
	v_mul_f32_e32 v0, v3, v41
	v_fma_f32 v0, v2, v33, -v0
	v_mul_f32_e32 v27, v42, v0
	v_mul_f32_e32 v0, v3, v33
	v_mul_f32_e32 v7, v42, v7
	v_fmac_f32_e32 v0, v2, v41
	v_mul_f32_e32 v43, v42, v43
	v_mul_f32_e32 v23, v42, v23
	v_mul_f32_e32 v25, v42, v25
	v_mul_f32_e32 v9, v42, v9
	v_mul_f32_e32 v11, v42, v11
	v_mul_f32_e32 v5, v42, v5
	v_mul_f32_e32 v26, v42, v1
	v_mul_f32_e32 v28, v42, v0
	v_cvt_pk_bf16_f32 v0, v43, v23
	v_cvt_pk_bf16_f32 v1, v25, v9
	v_cvt_pk_bf16_f32 v2, v11, v5
	v_cvt_pk_bf16_f32 v3, v7, v27
	v_mul_lo_u32 v7, v13, s66
	v_add3_u32 v5, 32, v7, v160
	v_mov_b32_e32 v13, v161
	ds_write_b128 v5, v[0:3]
	v_cvt_pk_bf16_f32 v0, v22, v24
	v_cvt_pk_bf16_f32 v1, v8, v10
	v_cvt_pk_bf16_f32 v2, v4, v6
	v_cvt_pk_bf16_f32 v3, v26, v28
	ds_write_b128 v5, v[0:3] offset:128
	v_lshl_add_u64 v[4:5], v[16:17], 0, v[12:13]
	v_add_u32_e32 v6, v19, v7
	s_waitcnt vmcnt(9)
	v_mov_b32_e32 v0, v124
	v_mov_b32_e32 v1, v125
	v_mov_b32_e32 v2, v126
	v_mov_b32_e32 v3, v127
	ds_write_b128 v6, v[0:3] offset:34816
	s_waitcnt vmcnt(8)
	v_mov_b32_e32 v0, v128
	v_mov_b32_e32 v1, v129
	v_mov_b32_e32 v2, v130
	v_mov_b32_e32 v3, v131
	ds_write_b128 v6, v[0:3] offset:34832
	v_add_u32_e32 v0, 0x200, v18
	v_ashrrev_i32_e32 v24, 3, v0
	v_add_u32_e32 v0, s11, v24
	v_mad_i64_i32 v[0:1], s[0:1], v0, s65, v[14:15]
	v_lshl_add_u64 v[0:1], v[0:1], 0, s[2:3]
	v_lshl_add_u64 v[6:7], v[0:1], 0, v[160:161]
	s_and_b32 s0, s8, 0x3ff00
	s_lshl_b32 s1, s10, 2
	s_or_b32 s0, s1, s0
	s_or_b32 s0, s0, s9
	s_lshl_b32 s2, s0, 14
	s_lshl_b64 s[0:1], s[2:3], 1
	v_readlane_b32 s2, v253, 28
	s_add_u32 s0, s2, s0
	v_readlane_b32 s2, v253, 29
	s_addc_u32 s1, s2, s1
	s_waitcnt vmcnt(7)
	v_mov_b32_e32 v2, v132
	v_mov_b32_e32 v3, v133
	v_mov_b32_e32 v4, v134
	v_mov_b32_e32 v5, v135
	v_lshlrev_b32_e32 v25, 16, v2
	v_and_b32_e32 v26, 0xffff0000, v2
	v_lshlrev_b32_e32 v27, 16, v3
	v_and_b32_e32 v28, 0xffff0000, v3
	v_lshlrev_b32_e32 v29, 16, v4
	v_and_b32_e32 v30, 0xffff0000, v4
	v_lshlrev_b32_e32 v31, 16, v5
	v_and_b32_e32 v32, 0xffff0000, v5
	s_waitcnt vmcnt(6)
	v_mov_b32_e32 v2, v136
	v_mov_b32_e32 v3, v137
	v_mov_b32_e32 v4, v138
	v_mov_b32_e32 v5, v139
	v_lshlrev_b32_e32 v33, 16, v2
	v_and_b32_e32 v34, 0xffff0000, v2
	v_sub_u32_e32 v2, 0x7f, v24
	v_cvt_f32_i32_e32 v2, v2
	v_lshlrev_b32_e32 v35, 16, v3
	v_and_b32_e32 v36, 0xffff0000, v3
	v_lshlrev_b32_e32 v37, 16, v4
	v_mul_f32_e32 v2, v21, v2
	v_mul_f32_e32 v2, 0x3fb8aa3b, v2
	v_exp_f32_e32 v2, v2
	v_and_b32_e32 v38, 0xffff0000, v4
	v_lshlrev_b32_e32 v39, 16, v5
	v_and_b32_e32 v40, 0xffff0000, v5
	v_mul_f32_e32 v41, 0x3db504f3, v2
	v_lshl_or_b32 v2, v24, 6, v20
	v_ashrrev_i32_e32 v3, 31, v2
	v_lshl_add_u64 v[10:11], v[2:3], 3, s[4:5]
	s_waitcnt vmcnt(2)
	v_mov_b32_e32 v2, v140
	v_mov_b32_e32 v3, v141
	v_mov_b32_e32 v4, v142
	v_mov_b32_e32 v5, v143
	v_mov_b32_e32 v6, v144
	v_mov_b32_e32 v7, v145
	v_mov_b32_e32 v8, v146
	v_mov_b32_e32 v9, v147
	v_mov_b32_e32 v14, v148
	v_mov_b32_e32 v15, v149
	v_mov_b32_e32 v16, v150
	v_mov_b32_e32 v17, v151
	v_mov_b32_e32 v20, v152
	v_mov_b32_e32 v21, v153
	v_mov_b32_e32 v22, v154
	v_mov_b32_e32 v23, v155
	v_mul_f32_e32 v10, v21, v33
	v_mul_f32_e32 v11, v21, v25
	v_fma_f32 v10, v20, v25, -v10
	v_fmac_f32_e32 v11, v20, v33
	v_mul_f32_e32 v20, v23, v34
	v_mul_f32_e32 v21, v23, v26
	v_fma_f32 v20, v22, v26, -v20
	v_fmac_f32_e32 v21, v22, v34
	v_mul_f32_e32 v22, v15, v35
	v_mul_f32_e32 v15, v15, v27
	v_fmac_f32_e32 v15, v14, v35
	v_fma_f32 v22, v14, v27, -v22
	v_mul_f32_e32 v14, v41, v15
	v_mul_f32_e32 v15, v17, v36
	v_mul_f32_e32 v17, v17, v28
	v_fmac_f32_e32 v17, v16, v36
	v_fma_f32 v15, v16, v28, -v15
	v_mul_f32_e32 v16, v41, v17
	v_mul_f32_e32 v17, v7, v37
	v_mul_f32_e32 v7, v7, v29
	v_fmac_f32_e32 v7, v6, v37
	v_fma_f32 v17, v6, v29, -v17
	v_mul_f32_e32 v6, v41, v7
	v_mul_f32_e32 v7, v9, v38
	v_mul_f32_e32 v9, v9, v30
	v_fmac_f32_e32 v9, v8, v38
	v_fma_f32 v7, v8, v30, -v7
	v_mul_f32_e32 v8, v41, v9
	v_mul_f32_e32 v9, v3, v39
	v_mul_f32_e32 v3, v3, v31
	v_fma_f32 v9, v2, v31, -v9
	v_fmac_f32_e32 v3, v2, v39
	v_mul_f32_e32 v2, v5, v40
	v_fma_f32 v2, v4, v32, -v2
	v_mul_f32_e32 v25, v41, v2
	v_mul_f32_e32 v2, v5, v32
	v_mul_f32_e32 v7, v41, v7
	v_fmac_f32_e32 v2, v4, v40
	v_mul_f32_e32 v10, v41, v10
	v_mul_f32_e32 v20, v41, v20
	v_mul_f32_e32 v22, v41, v22
	v_mul_f32_e32 v15, v41, v15
	v_mul_f32_e32 v17, v41, v17
	v_mul_f32_e32 v9, v41, v9
	v_mul_f32_e32 v23, v41, v3
	v_mul_f32_e32 v26, v41, v2
	v_cvt_pk_bf16_f32 v2, v10, v20
	v_cvt_pk_bf16_f32 v3, v22, v15
	v_cvt_pk_bf16_f32 v4, v17, v7
	v_mul_lo_u32 v7, v24, s66
	v_cvt_pk_bf16_f32 v5, v9, v25
	v_add3_u32 v9, 32, v7, v160
	v_mul_f32_e32 v11, v41, v11
	v_mul_f32_e32 v21, v41, v21
	ds_write_b128 v9, v[2:5]
	v_cvt_pk_bf16_f32 v2, v11, v21
	v_cvt_pk_bf16_f32 v3, v14, v16
	v_cvt_pk_bf16_f32 v4, v6, v8
	v_cvt_pk_bf16_f32 v5, v23, v26
	ds_write_b128 v9, v[2:5] offset:128
	v_lshl_add_u64 v[4:5], v[0:1], 0, v[12:13]
	v_add_u32_e32 v6, v19, v7
	s_waitcnt vmcnt(1)
	v_mov_b32_e32 v0, v156
	v_mov_b32_e32 v1, v157
	v_mov_b32_e32 v2, v158
	v_mov_b32_e32 v3, v159
	ds_write_b128 v6, v[0:3] offset:34816
	v_ashrrev_i32_e32 v4, 6, v18
	v_and_b32_e32 v5, 15, v18
	v_lshlrev_b32_e32 v5, 7, v5
	s_waitcnt vmcnt(0)
	v_mov_b32_e32 v0, v204
	v_mov_b32_e32 v1, v205
	v_mov_b32_e32 v2, v206
	v_mov_b32_e32 v3, v207
	ds_write_b128 v6, v[0:3] offset:34832
	v_lshrrev_b32_e32 v0, 1, v18
	v_and_b32_e32 v160, 24, v0
	v_bfe_u32 v0, v18, 2, 2
	v_or_b32_e32 v0, v160, v0
	v_lshlrev_b32_e32 v1, 3, v18
	v_mul_u32_u24_e32 v0, 0x88, v0
	v_and_b32_e32 v1, 24, v1
	v_lshlrev_b32_e32 v0, 1, v0
	v_add3_u32 v6, 32, v1, v0
	v_lshl_add_u32 v7, v4, 5, v6
	s_waitcnt lgkmcnt(0)
	s_barrier
; DI f32x4 mmaT(bf16x8 a_m, bf16x8 b_n, f32x4 c) { return __builtin_amdgcn_mfma_f32_16x16x32_bf16(b_n, a_m, c, 0, 0, 0); }
; DI void ret_local_unit(const Params& p, int hf, int bl, int c, int hd, unsigned char* shm, int tid) {
;     ...
;   const int wid = tid >> 6, lane = tid & 63, fr = lane & 15, fq = lane >> 4;
;   f32x4 acc[8];
; #pragma unroll
;   for (int n = 0; n < 8; ++n) acc[n] = (f32x4){0.f, 0.f, 0.f, 0.f};
; #pragma unroll
;   for (int ks = 0; ks < 4; ++ks) {
;     const bf16x8 a = frag_tr(sV, LD, 32 * ks, 16 * wid, fr, fq);
; #pragma unroll
;     for (int n = 0; n < 8; ++n) acc[n] = mmaT(a, frag_tr(sK, LD, 32 * ks, 16 * n, fr, fq), acc[n]);
;   }
	ds_read_b64_tr_b16 v[0:1], v7 offset:34816
	ds_read_b64_tr_b16 v[2:3], v7 offset:35904
	ds_read_b64_tr_b16 v[10:11], v6 offset:1088
	ds_read_b64_tr_b16 v[8:9], v6
	ds_read_b64_tr_b16 v[12:13], v6 offset:32
	ds_read_b64_tr_b16 v[14:15], v6 offset:1120
	ds_read_b64_tr_b16 v[16:17], v6 offset:64
	ds_read_b64_tr_b16 v[18:19], v6 offset:1152
	ds_read_b64_tr_b16 v[20:21], v6 offset:96
	ds_read_b64_tr_b16 v[22:23], v6 offset:1184
	ds_read_b64_tr_b16 v[24:25], v6 offset:128
	ds_read_b64_tr_b16 v[26:27], v6 offset:1216
	ds_read_b64_tr_b16 v[28:29], v6 offset:160
	ds_read_b64_tr_b16 v[30:31], v6 offset:1248
	ds_read_b64_tr_b16 v[32:33], v6 offset:192
	ds_read_b64_tr_b16 v[34:35], v6 offset:1280
	ds_read_b64_tr_b16 v[36:37], v6 offset:224
	ds_read_b64_tr_b16 v[38:39], v6 offset:1312
	s_waitcnt lgkmcnt(14)
	v_mfma_f32_16x16x32_bf16 v[8:11], v[8:11], v[0:3], 0
	v_lshl_or_b32 v4, v4, 11, v5
	v_ashrrev_i32_e32 v5, 31, v4
	v_lshl_add_u64 v[4:5], v[4:5], 1, s[0:1]
	s_waitcnt lgkmcnt(12)
	v_mfma_f32_16x16x32_bf16 v[12:15], v[12:15], v[0:3], 0
	v_lshl_add_u64 v[4:5], v[4:5], 0, v[160:161]
	s_mov_b64 s[0:1], 0
	s_waitcnt lgkmcnt(10)
	v_mfma_f32_16x16x32_bf16 v[16:19], v[16:19], v[0:3], 0
	s_waitcnt lgkmcnt(8)
	v_mfma_f32_16x16x32_bf16 v[20:23], v[20:23], v[0:3], 0
	s_waitcnt lgkmcnt(6)
	v_mfma_f32_16x16x32_bf16 v[24:27], v[24:27], v[0:3], 0
	s_waitcnt lgkmcnt(4)
	v_mfma_f32_16x16x32_bf16 v[28:31], v[28:31], v[0:3], 0
	s_waitcnt lgkmcnt(2)
	v_mfma_f32_16x16x32_bf16 v[32:35], v[32:35], v[0:3], 0
	s_waitcnt lgkmcnt(0)
	v_mfma_f32_16x16x32_bf16 v[0:3], v[36:39], v[0:3], 0
	ds_read_b64_tr_b16 v[36:37], v7 offset:43520
	ds_read_b64_tr_b16 v[38:39], v7 offset:44608
	ds_read_b64_tr_b16 v[40:41], v6 offset:8704
	ds_read_b64_tr_b16 v[42:43], v6 offset:9792
	s_waitcnt lgkmcnt(0)
	v_mfma_f32_16x16x32_bf16 v[8:11], v[40:43], v[36:39], v[8:11]
	ds_read_b64_tr_b16 v[40:41], v6 offset:8736
	ds_read_b64_tr_b16 v[42:43], v6 offset:9824
	s_waitcnt lgkmcnt(0)
	v_mfma_f32_16x16x32_bf16 v[12:15], v[40:43], v[36:39], v[12:15]
	ds_read_b64_tr_b16 v[40:41], v6 offset:8768
	ds_read_b64_tr_b16 v[42:43], v6 offset:9856
	s_waitcnt lgkmcnt(0)
	v_mfma_f32_16x16x32_bf16 v[16:19], v[40:43], v[36:39], v[16:19]
	ds_read_b64_tr_b16 v[40:41], v6 offset:8800
	ds_read_b64_tr_b16 v[42:43], v6 offset:9888
	s_waitcnt lgkmcnt(0)
	v_mfma_f32_16x16x32_bf16 v[20:23], v[40:43], v[36:39], v[20:23]
	ds_read_b64_tr_b16 v[40:41], v6 offset:8832
	ds_read_b64_tr_b16 v[42:43], v6 offset:9920
	s_waitcnt lgkmcnt(0)
	v_mfma_f32_16x16x32_bf16 v[24:27], v[40:43], v[36:39], v[24:27]
	ds_read_b64_tr_b16 v[40:41], v6 offset:8864
	ds_read_b64_tr_b16 v[42:43], v6 offset:9952
	s_waitcnt lgkmcnt(0)
	v_mfma_f32_16x16x32_bf16 v[28:31], v[40:43], v[36:39], v[28:31]
	ds_read_b64_tr_b16 v[40:41], v6 offset:8896
	ds_read_b64_tr_b16 v[42:43], v6 offset:9984
	s_waitcnt lgkmcnt(0)
	v_mfma_f32_16x16x32_bf16 v[32:35], v[40:43], v[36:39], v[32:35]
	ds_read_b64_tr_b16 v[40:41], v6 offset:8928
	ds_read_b64_tr_b16 v[42:43], v6 offset:10016
	s_waitcnt lgkmcnt(0)
	v_mfma_f32_16x16x32_bf16 v[0:3], v[40:43], v[36:39], v[0:3]
	ds_read_b64_tr_b16 v[36:37], v7 offset:52224
	ds_read_b64_tr_b16 v[38:39], v7 offset:53312
	ds_read_b64_tr_b16 v[40:41], v6 offset:17408
	ds_read_b64_tr_b16 v[42:43], v6 offset:18496
	s_waitcnt lgkmcnt(0)
	v_mfma_f32_16x16x32_bf16 v[8:11], v[40:43], v[36:39], v[8:11]
	ds_read_b64_tr_b16 v[40:41], v6 offset:17440
	ds_read_b64_tr_b16 v[42:43], v6 offset:18528
	s_waitcnt lgkmcnt(0)
; DI unsigned pk2(float lo, float hi) { unsigned r; asm volatile("v_cvt_pk_bf16_f32 %0, %1, %2" : "=v"(r) : "v"(lo), "v"(hi)); return r; }
; DI f32x4 mmaT(bf16x8 a_m, bf16x8 b_n, f32x4 c) { return __builtin_amdgcn_mfma_f32_16x16x32_bf16(b_n, a_m, c, 0, 0, 0); }
; DI void ret_local_unit(const Params& p, int hf, int bl, int c, int hd, unsigned char* shm, int tid) {
;     ...
; #pragma unroll
;   for (int ks = 0; ks < 4; ++ks) {
;     const bf16x8 a = frag_tr(sV, LD, 32 * ks, 16 * wid, fr, fq);
; #pragma unroll
;     for (int n = 0; n < 8; ++n) acc[n] = mmaT(a, frag_tr(sK, LD, 32 * ks, 16 * n, fr, fq), acc[n]);
;   }
;   bf16_t* st = (bf16_t*)(wsb + WS_RST) + (size_t)((bl * 64 + c) * 4 + hd) * 16384;
; #pragma unroll
;   for (int n = 0; n < 8; ++n) { uint2 w; w.x = pk2(acc[n][0], acc[n][1]); w.y = pk2(acc[n][2], acc[n][3]); *(uint2*)(st + (16 * wid + fr) * 128 + 16 * n + 4 * fq) = w; }
;   __syncthreads();
	v_mfma_f32_16x16x32_bf16 v[12:15], v[40:43], v[36:39], v[12:15]
	ds_read_b64_tr_b16 v[40:41], v6 offset:17472
	ds_read_b64_tr_b16 v[42:43], v6 offset:18560
	s_waitcnt lgkmcnt(0)
	v_mfma_f32_16x16x32_bf16 v[16:19], v[40:43], v[36:39], v[16:19]
	ds_read_b64_tr_b16 v[40:41], v6 offset:17504
	ds_read_b64_tr_b16 v[42:43], v6 offset:18592
	s_waitcnt lgkmcnt(0)
	v_mfma_f32_16x16x32_bf16 v[20:23], v[40:43], v[36:39], v[20:23]
	ds_read_b64_tr_b16 v[40:41], v6 offset:17536
	ds_read_b64_tr_b16 v[42:43], v6 offset:18624
	s_waitcnt lgkmcnt(0)
	v_mfma_f32_16x16x32_bf16 v[24:27], v[40:43], v[36:39], v[24:27]
	ds_read_b64_tr_b16 v[40:41], v6 offset:17568
	ds_read_b64_tr_b16 v[42:43], v6 offset:18656
	s_waitcnt lgkmcnt(0)
	v_mfma_f32_16x16x32_bf16 v[28:31], v[40:43], v[36:39], v[28:31]
	ds_read_b64_tr_b16 v[40:41], v6 offset:17600
	ds_read_b64_tr_b16 v[42:43], v6 offset:18688
	s_waitcnt lgkmcnt(0)
	v_mfma_f32_16x16x32_bf16 v[32:35], v[40:43], v[36:39], v[32:35]
	ds_read_b64_tr_b16 v[40:41], v6 offset:17632
	ds_read_b64_tr_b16 v[42:43], v6 offset:18720
	s_waitcnt lgkmcnt(0)
	v_mfma_f32_16x16x32_bf16 v[0:3], v[40:43], v[36:39], v[0:3]
	ds_read_b64_tr_b16 v[36:37], v7 offset:60928
	ds_read_b64_tr_b16 v[38:39], v7 offset:62016
	ds_read_b64_tr_b16 v[40:41], v6 offset:26112
	ds_read_b64_tr_b16 v[42:43], v6 offset:27200
	s_waitcnt lgkmcnt(0)
	v_mfma_f32_16x16x32_bf16 v[8:11], v[40:43], v[36:39], v[8:11]
	ds_read_b64_tr_b16 v[40:41], v6 offset:26144
	ds_read_b64_tr_b16 v[42:43], v6 offset:27232
	s_waitcnt lgkmcnt(0)
	v_mfma_f32_16x16x32_bf16 v[12:15], v[40:43], v[36:39], v[12:15]
	ds_read_b64_tr_b16 v[40:41], v6 offset:26176
	ds_read_b64_tr_b16 v[42:43], v6 offset:27264
	s_waitcnt lgkmcnt(0)
	v_mfma_f32_16x16x32_bf16 v[16:19], v[40:43], v[36:39], v[16:19]
	ds_read_b64_tr_b16 v[40:41], v6 offset:26208
	ds_read_b64_tr_b16 v[42:43], v6 offset:27296
	s_waitcnt lgkmcnt(0)
	v_mfma_f32_16x16x32_bf16 v[20:23], v[40:43], v[36:39], v[20:23]
	ds_read_b64_tr_b16 v[40:41], v6 offset:26240
	ds_read_b64_tr_b16 v[42:43], v6 offset:27328
	s_waitcnt lgkmcnt(0)
	v_mfma_f32_16x16x32_bf16 v[24:27], v[40:43], v[36:39], v[24:27]
	ds_read_b64_tr_b16 v[40:41], v6 offset:26272
	ds_read_b64_tr_b16 v[42:43], v6 offset:27360
	s_waitcnt lgkmcnt(0)
	v_mfma_f32_16x16x32_bf16 v[28:31], v[40:43], v[36:39], v[28:31]
	ds_read_b64_tr_b16 v[40:41], v6 offset:26304
	ds_read_b64_tr_b16 v[42:43], v6 offset:27392
	s_waitcnt lgkmcnt(0)
	v_mfma_f32_16x16x32_bf16 v[32:35], v[40:43], v[36:39], v[32:35]
	ds_read_b64_tr_b16 v[40:41], v6 offset:26336
	ds_read_b64_tr_b16 v[42:43], v6 offset:27424
	v_cvt_pk_bf16_f32 v6, v8, v9
	v_cvt_pk_bf16_f32 v7, v10, v11
	global_store_dwordx2 v[4:5], v[6:7], off
	v_cvt_pk_bf16_f32 v6, v12, v13
	v_cvt_pk_bf16_f32 v7, v14, v15
	global_store_dwordx2 v[4:5], v[6:7], off offset:32
	v_cvt_pk_bf16_f32 v6, v16, v17
	v_cvt_pk_bf16_f32 v7, v18, v19
	global_store_dwordx2 v[4:5], v[6:7], off offset:64
	v_cvt_pk_bf16_f32 v6, v20, v21
	v_cvt_pk_bf16_f32 v7, v22, v23
	global_store_dwordx2 v[4:5], v[6:7], off offset:96
	v_cvt_pk_bf16_f32 v6, v24, v25
	v_cvt_pk_bf16_f32 v7, v26, v27
	s_waitcnt lgkmcnt(0)
	v_mfma_f32_16x16x32_bf16 v[0:3], v[40:43], v[36:39], v[0:3]
	global_store_dwordx2 v[4:5], v[6:7], off offset:128
	v_cvt_pk_bf16_f32 v6, v28, v29
	v_cvt_pk_bf16_f32 v7, v30, v31
	global_store_dwordx2 v[4:5], v[6:7], off offset:160
	v_cvt_pk_bf16_f32 v6, v32, v33
	v_cvt_pk_bf16_f32 v7, v34, v35
	global_store_dwordx2 v[4:5], v[6:7], off offset:192
	v_cvt_pk_bf16_f32 v0, v0, v1
	v_cvt_pk_bf16_f32 v1, v2, v3
	s_nop 4
	global_store_dwordx2 v[4:5], v[0:1], off offset:224
	s_barrier
